# first grid barrier: acquire invalidate issued in front of the P0 store drain instead of behind the arrive atomic
# baseline (speedup 1.0000x reference)
; __device__ __forceinline__ unsigned xb_ld(unsigned* p)              { return __hip_atomic_load(p, __ATOMIC_RELAXED, __HIP_MEMORY_SCOPE_AGENT); }
; __device__ __forceinline__ unsigned xb_add(unsigned* p, unsigned v) { return __hip_atomic_fetch_add(p, v, __ATOMIC_RELAXED, __HIP_MEMORY_SCOPE_AGENT); }
; #define XB_SPIN(cond, bar) do { unsigned _sp = 0; while (cond) { __builtin_amdgcn_s_sleep(1); \
;     if ((++_sp & 255u) == 0u) { if (xb_ld(&(bar)[XB_TMO])) break; if (_sp > XB_SPIN_CAP) { atomicAdd(&(bar)[XB_TMO], 1u); break; } } } } while (0)
; __device__ __forceinline__ void xcd_barrier(const XcdBarrier& b) {
;     asm volatile("s_waitcnt vmcnt(0)" ::: "memory");
;     __syncthreads();
;     if (threadIdx.x == 0) {
;         unsigned* bar = b.bar;
;         __builtin_amdgcn_s_waitcnt(0);
;         unsigned nloc = b.st[0], nx = b.st[1];
;         if (nloc == 0u) { xcd_barrier_complete(bar, b.x, nloc, nx); b.st[0] = nloc; b.st[1] = nx; }
;         const unsigned old = xb_add(&bar[XB_XSUB(b.x)], 1u);
;         const unsigned gen = old / nloc;
;         if (old + 1u == (gen + 1u) * nloc) {
;             __builtin_amdgcn_fence(__ATOMIC_RELEASE, "agent");
;             asm volatile("s_waitcnt vmcnt(0)" ::: "memory");
;             const unsigned og = xb_add(&bar[XB_TOP], 1u);
;             const unsigned tg = og / nx;
;             if (og + 1u == (tg + 1u) * nx) {
; #pragma unroll
;                 for (unsigned jx = 0; jx < 16; ++jx) (void)xb_add(&bar[XB_XGEN(jx)], 1u);
;             }
;         }
;         XB_SPIN(xb_ld(&bar[XB_XGEN(b.x)]) == gen, bar);
;         __builtin_amdgcn_fence(__ATOMIC_ACQUIRE, "agent");
;         asm volatile("s_waitcnt vmcnt(0)" ::: "memory");
.LBB0_32:
	s_mov_b64 s[100:101], exec
	s_and_b64 exec, exec, s[62:63]
	s_cbranch_execz .Lp0_inv_skip
	buffer_inv sc1
